# stack: wide attention epilogue + peeled GEMM first trip (no accumulator clears) + MLP-up epilogue self-max removed
# speedup vs baseline: 1.0101x; 1.0001x over previous
; #define PG8_WAIT_V(n) asm volatile("s_waitcnt vmcnt(" #n ")" ::: "memory")
;     __host__ __device__ bool next(int i, Unit& u) const {
;         const long L = (long)i * G + c; if (L >= nwg) return false;
;         int wgid = (int)L; { const int q = nwg / NXCD, r = nwg % NXCD, xcd = wgid % NXCD, off = wgid / NXCD; wgid = (xcd < r ? xcd * (q + 1) : r * (q + 1) + (xcd - r) * q) + off; }
;         const int nig = wgm * nN, gid = wgid / nig, fm = gid * wgm, gsz = (nM - fm) < wgm ? (nM - fm) : wgm;
;         u.pm = fm + ((wgid % nig) % gsz); u.pn = (wgid % nig) / gsz; if (rev) u.pm = nM - 1 - u.pm; return true;
; template <class Epi, class Sched, bool ALIGN_EPI = false, bool SP2 = false>
; __device__ __forceinline__ void gemm_phase(PG8_LAS unsigned char* lds, const Gemm g, const Sched& S, const Epi& E) {
;     ...
;     const int tid = tid_, wid = __builtin_amdgcn_readfirstlane(tid >> 6), lane = tid & 63, wr = wid >> 2, wc = wid & 3, fr = lane & 15, fq = lane >> 4;
;     const int K = g.K, nt = K / BK;
;     unsigned voffA[2], voffB[2];
; #pragma unroll
;     for (int i = 0; i < 2; ++i) { int R, C; stage_rc(tid * 16 + i * 8192, R, C); const int Rb = Epi::PERM ? ((R & ~31) + perm32(R & 31)) : R;
;         voffA[i] = (unsigned)(R * K + C) * 2u; voffB[i] = (unsigned)(Rb * K + C) * 2u; }
;     const size_t kstep = (size_t)(BK * 2);
;     const size_t hstep = (size_t)HALF * K * 2;
;     const size_t tstep = 2 * hstep;
;     const unsigned ldsw = (unsigned)wid * 1024u;
;     const int aoff = lds_byte(wr * 64 + fr, fq * 8), boff = lds_byte(wc * 32 + fr, fq * 8);
;     ...
;     Unit cur, nxt; int ui = 0;
;     if (!S.next(0, cur)) return;
;     f32x4 acc[2][2][4][2];
; #pragma unroll
;     for (int a = 0; a < 2; ++a)
; #pragma unroll
;         for (int b = 0; b < 2; ++b)
; #pragma unroll
;             for (int m = 0; m < 4; ++m)
; #pragma unroll
;                 for (int n = 0; n < 2; ++n) acc[a][b][m][n] = (f32x4){0.f, 0.f, 0.f, 0.f};
;     bf16x8 At[4][2], B0[2][2], B1[2][2];
;     const char* cA = (const char*)g.A + (size_t)cur.pm * tstep; const char* cB = (const char*)g.Bt + (size_t)cur.pn * tstep;
;     S.a_ready(cur);
;     if constexpr (SP2) {
;         PG8_STAGE(PG8_SB(0, 0), cB, voffB); PG8_STAGE(PG8_SB(0, 1), cB + hstep, voffB); PG8_STAGE(PG8_SA(0, 0), cA, voffA); PG8_STAGE(PG8_SA(0, 1), cA + hstep, voffA);
;         if (wr == 1) PG8_BAR;
;         PG8_WAIT_V(2); PG8_BAR;
.LBB0_540:
	s_or_b64 exec, exec, s[14:15]
	s_nop 0
	s_nop 0
	s_nop 0
	s_nop 0
	s_nop 0
	s_nop 0
	s_nop 0
	s_nop 0
	s_nop 0
	s_nop 0
	s_nop 0
	s_nop 0
	s_nop 0
	s_nop 0
	s_nop 0
	s_nop 0
	s_cmpk_lt_i32 s2, 0x400
	s_mov_b64 s[22:23], s[0:1]
	s_mov_b64 s[16:17], s[0:1]
	s_mov_b64 s[24:25], s[0:1]
	s_mov_b64 s[18:19], s[0:1]
	s_mov_b64 s[14:15], s[0:1]
	s_waitcnt lgkmcnt(0)
	s_barrier
	s_cselect_b64 s[48:49], -1, 0
	s_lshr_b32 s13, s33, 29
	s_add_i32 s13, s2, s13
	s_load_dwordx2 s[14:15], s[14:15], 0xc8
	s_ashr_i32 s56, s13, 3
	s_and_b32 s13, s13, -8
	s_load_dwordx2 s[20:21], s[16:17], 0xc8
	s_nop 0
	s_load_dwordx2 s[18:19], s[18:19], 0xc8
	s_mov_b64 s[16:17], s[0:1]
	s_sub_i32 s59, s2, s13
	s_cmp_lt_i32 s59, 0
	s_load_dwordx2 s[16:17], s[16:17], 0xc8
	s_cselect_b64 s[42:43], -1, 0
	s_lshl_b32 s57, s59, 7
	s_waitcnt lgkmcnt(0)
	s_add_u32 s14, s14, 0x2f800000
	s_addc_u32 s15, s15, 0
	s_waitcnt vmcnt(27)
	v_mov_b32_e32 v14, v216
	s_cmpk_gt_i32 s2, 0x3ff
	s_mul_i32 s58, s59, 0x81
	s_nop 0
	v_readfirstlane_b32 s28, v14
	s_cbranch_scc1 .LBB0_560
	v_lshlrev_b32_e32 v0, 4, v14
	v_add_u32_e32 v1, 0x2000, v0
	v_ashrrev_i32_e32 v2, 31, v1
	v_lshrrev_b32_e32 v2, 22, v2
	v_add_u32_e32 v2, v1, v2
	v_ashrrev_i32_e32 v8, 10, v2
	v_mul_i32_i24_e32 v2, 0x400, v8
	v_sub_u32_e32 v1, v1, v2
	v_lshrrev_b32_e32 v2, 4, v1
	v_bitop3_b32 v1, v2, v1, 32 bitop3:0x6c
	v_ashrrev_i32_e32 v2, 31, v1
	s_load_dwordx2 s[22:23], s[22:23], 0xc8
	s_nop 0
	s_load_dwordx2 s[24:25], s[24:25], 0xc8
	v_lshrrev_b32_e32 v2, 26, v2
	v_add_u32_e32 v2, v1, v2
	v_lshlrev_b32_e32 v3, 3, v8
	v_ashrrev_i32_e32 v9, 6, v2
	v_and_b32_e32 v3, -16, v3
	v_add_u32_e32 v3, v9, v3
	s_waitcnt lgkmcnt(0)
	s_add_u32 s13, s22, 0x3b800000
	v_and_b32_e32 v4, 3, v9
	s_mov_b32 s22, 0x1fffe0
	v_lshrrev_b32_e32 v5, 2, v3
	v_lshlrev_b32_e32 v6, 1, v3
	v_and_b32_e32 v2, 0xc0, v2
	v_and_or_b32 v4, v3, s22, v4
	v_and_b32_e32 v5, 4, v5
	v_and_b32_e32 v6, 24, v6
	v_sub_u32_e32 v1, v1, v2
	v_mov_b32_e32 v2, 1
	v_or3_b32 v4, v4, v5, v6
	v_lshlrev_b32_e32 v5, 5, v8
	v_ashrrev_i16_sdwa v1, v2, sext(v1) dst_sel:DWORD dst_unused:UNUSED_PAD src0_sel:DWORD src1_sel:BYTE_0
	v_and_b32_e32 v5, 32, v5
	v_bfe_i32 v10, v1, 0, 16
	v_add_lshl_u32 v1, v5, v10, 1
	s_waitcnt vmcnt(6)
	v_lshl_add_u32 v152, v4, 11, v1
	v_lshl_add_u32 v154, v3, 11, v1
	v_bfe_i32 v1, v14, 27, 1
	v_lshrrev_b32_e32 v1, 22, v1
	v_add_u32_e32 v1, v0, v1
	v_and_b32_e32 v1, 0xfffffc00, v1
	v_sub_u32_e32 v0, v0, v1
	v_lshrrev_b32_e32 v1, 4, v0
	v_ashrrev_i32_e32 v3, 31, v14
	v_bitop3_b32 v0, v1, v0, 32 bitop3:0x6c
	v_lshrrev_b32_e32 v3, 26, v3
	v_ashrrev_i32_e32 v1, 31, v0
	v_add_u32_e32 v3, v14, v3
	s_addc_u32 s47, s23, 0
	v_lshrrev_b32_e32 v1, 26, v1
	v_ashrrev_i32_e32 v12, 6, v3
	s_add_u32 s60, s24, 0x2600000
	v_add_u32_e32 v1, v0, v1
	v_lshlrev_b32_e32 v3, 3, v12
	s_addc_u32 s61, s25, 0
	s_ashr_i32 s26, s28, 6
	v_ashrrev_i32_e32 v11, 6, v1
	v_and_b32_e32 v3, -16, v3
	s_ashr_i32 s27, s28, 8
	s_lshl_b32 s62, s26, 10
	v_add_u32_e32 v3, v11, v3
	v_and_b32_e32 v4, 3, v11
	v_and_or_b32 v4, v3, s22, v4
	s_and_b64 s[22:23], s[42:43], exec
	s_cselect_b32 s22, s58, s57
	s_add_i32 s22, s22, s56
	s_ashr_i32 s23, s22, 31
	s_lshr_b32 s23, s23, 27
	s_add_i32 s23, s22, s23
	s_ashr_i32 s24, s23, 5
	s_and_b32 s23, s23, 0xffe0
	s_sub_i32 s22, s22, s23
	s_bfe_i32 s23, s22, 0x80000
	s_bfe_u32 s23, s23, 0x2000d
	s_add_i32 s23, s22, s23
	s_lshl_b32 s25, s24, 2
	s_bfe_i32 s24, s23, 0x80000
	s_and_b32 s23, s23, 0xfc
	s_sub_i32 s22, s22, s23
	s_sext_i32_i16 s24, s24
	s_sext_i32_i8 s22, s22
	v_lshrrev_b32_e32 v5, 2, v3
	v_lshlrev_b32_e32 v6, 1, v3
	v_and_b32_e32 v1, 0xc0, v1
	s_lshr_b32 s24, s24, 2
	s_add_i32 s44, s25, s22
	v_and_b32_e32 v5, 4, v5
	v_and_b32_e32 v6, 24, v6
	v_sub_u32_e32 v0, v0, v1
	s_ashr_i32 s45, s44, 31
	s_bfe_i64 s[30:31], s[24:25], 0x100000
	v_or3_b32 v4, v4, v5, v6
	v_lshlrev_b32_e32 v5, 5, v12
	v_ashrrev_i16_sdwa v0, v2, sext(v0) dst_sel:DWORD dst_unused:UNUSED_PAD src0_sel:DWORD src1_sel:BYTE_0
	s_lshl_b64 s[22:23], s[44:45], 19
	s_lshl_b64 s[30:31], s[30:31], 19
	v_and_b32_e32 v5, 32, v5
	v_bfe_i32 v13, v0, 0, 16
	s_add_u32 s52, s60, s30
	v_add_lshl_u32 v0, v5, v13, 1
	s_addc_u32 s53, s61, s31
	s_add_i32 s63, s62, 0
	v_lshl_add_u32 v156, v4, 11, v0
	s_add_i32 m0, s63, 0x10000
	v_lshl_add_u32 v158, v3, 11, v0
	global_load_lds_dwordx4 v156, s[52:53]
	s_add_i32 m0, s63, 0x12000
	s_add_u32 s30, s52, 0x40000
	global_load_lds_dwordx4 v152, s[52:53]
	s_addc_u32 s31, s53, 0
	s_add_i32 m0, s63, 0x14000
	v_mov_b32_e32 v157, 0
	global_load_lds_dwordx4 v156, s[30:31]
	s_add_i32 m0, s63, 0x16000
	s_add_u32 s50, s13, s22
	s_addc_u32 s51, s47, s23
	s_add_i32 s64, s63, 0x2000
	global_load_lds_dwordx4 v152, s[30:31]
	s_mov_b32 m0, s63
	s_add_u32 s22, s50, 0x40000
	global_load_lds_dwordx4 v158, s[50:51]
	s_mov_b32 m0, s64
	s_addc_u32 s23, s51, 0
	s_add_i32 s65, s63, 0x4000
	global_load_lds_dwordx4 v154, s[50:51]
	s_mov_b32 m0, s65
	s_add_i32 s66, s63, 0x6000
	global_load_lds_dwordx4 v158, s[22:23]
	s_mov_b32 m0, s66
	v_mov_b32_e32 v153, v157
	global_load_lds_dwordx4 v154, s[22:23]
	v_mov_b32_e32 v159, v157
	v_mov_b32_e32 v155, v157
	s_cmp_eq_u32 s27, 1
	v_lshl_add_u64 v[6:7], s[52:53], 0, v[156:157]
	v_lshl_add_u64 v[4:5], s[52:53], 0, v[152:153]
	v_lshl_add_u64 v[0:1], s[50:51], 0, v[158:159]
	s_cselect_b64 s[22:23], -1, 0
	s_cmp_lg_u32 s27, 1
	v_lshl_add_u64 v[2:3], s[50:51], 0, v[154:155]
	s_cbranch_scc1 .LBB0_543
	s_barrier

; __device__ __forceinline__ unsigned xb_ld(unsigned* p)              { return __hip_atomic_load(p, __ATOMIC_RELAXED, __HIP_MEMORY_SCOPE_AGENT); }
; __device__ __forceinline__ void xcd_barrier_complete(unsigned* bar, unsigned x, unsigned& nloc, unsigned& nx) {
;     ...
;         if ((++sp & 255u) == 0u) { if (xb_ld(&bar[XB_TMO])) break; if (sp > XB_SPIN_CAP) { atomicAdd(&bar[XB_TMO], 1u); break; } }
.LBB0_829:
	s_or_b64 exec, exec, s[4:5]
	s_nop 0
	s_nop 0
	s_nop 0
	s_nop 0
	s_nop 0
	s_nop 0
	s_nop 0
	s_nop 0
	s_nop 0
	s_nop 0
	s_nop 0
	s_nop 0
	s_nop 0
	s_and_saveexec_b64 s[4:5], s[6:7]
	s_cbranch_execz .LBB0_831
	v_mov_b32_e32 v2, 1
	global_atomic_add v[0:1], v2, off
